# grid barrier: non-leader workgroups poll the cross-XCD release generation directly (one hop fewer)
# speedup vs baseline: 1.0707x; 1.0034x over previous
.LBB0_666:
	s_or_b64 exec, exec, s[14:15]
	v_cvt_f32_u32_e32 v5, v3
	s_waitcnt vmcnt(0)
	v_readfirstlane_b32 s2, v4
	v_sub_u32_e32 v4, 0, v3
	v_rcp_iflag_f32_e32 v5, v5
	v_add_u32_e32 v6, s2, v0
	v_mul_f32_e32 v5, 0x4f7ffffe, v5
	v_cvt_u32_f32_e32 v5, v5
	v_mul_lo_u32 v0, v4, v5
	v_mul_hi_u32 v0, v5, v0
	v_add_u32_e32 v0, v5, v0
	v_mul_hi_u32 v0, v6, v0
	v_mul_lo_u32 v4, v0, v3
	v_sub_u32_e32 v4, v6, v4
	v_add_u32_e32 v5, 1, v0
	v_cmp_ge_u32_e32 vcc, v4, v3
	s_nop 1
	v_cndmask_b32_e32 v0, v0, v5, vcc
	v_sub_u32_e32 v5, v4, v3
	v_cndmask_b32_e32 v4, v4, v5, vcc
	v_add_u32_e32 v5, 1, v0
	v_cmp_ge_u32_e32 vcc, v4, v3
	v_add_u32_e32 v4, 1, v6
	s_nop 0
	v_cndmask_b32_e32 v0, v0, v5, vcc
	v_mul_lo_u32 v5, v3, v0
	v_add_u32_e32 v3, v5, v3
	v_cmp_ne_u32_e32 vcc, v4, v3
	s_and_saveexec_b64 s[2:3], vcc
	s_xor_b64 s[12:13], exec, s[2:3]
	s_cbranch_execz .LBB0_680
	s_waitcnt lgkmcnt(0)
	v_mov_b32_e32 v2, 0x3500
	global_load_dword v2, v2, s[6:7] sc1
	s_add_u32 s16, s6, 0x3500
	s_addc_u32 s17, s7, 0
	s_waitcnt vmcnt(0)
	v_cmp_eq_u32_e32 vcc, v2, v0
	s_and_saveexec_b64 s[14:15], vcc
	s_cbranch_execz .LBB0_679
	s_mov_b32 s2, 1
	s_mov_b64 s[18:19], 0
	s_branch .LBB0_670
